# + m23: scan_p1 and sgu items renumbered to the XCD owning their tokens; the batch-1 in-proj -> scan_p1/sgu barrier becomes XCD-local without L2 write-back (invalidate kept); same placement guard
# speedup vs baseline: 1.0136x; 1.0051x over previous
; #define LAS __attribute__((address_space(3)))
; __device__ __forceinline__ void scan_p1_item(LAS unsigned char* lds, unsigned char* ws, int item, int tid_in, int wid, int lane_in) {
;     const int h = item / NSEG, seg = item % NSEG;
;     float* SEG = (float*)(ws + WS_SEG); float* DSEG = (float*)(ws + WS_DSEG);
;     const unsigned short* LFp = (const unsigned short*)(ws + WS_LF); const unsigned short* LBp = (const unsigned short*)(ws + WS_LB); const bf16* Vp = (const bf16*)(ws + WS_V);
;     constexpr int P_KF = 0, P_KB = 18432, P_VT = 36864, P_TOT = 55296, P_DV = 63488;
;     LAS float* TOT = (LAS float*)(lds + P_TOT); LAS float* DV = (LAS float*)(lds + P_DV);
;     int tid = tid_in, lane = lane_in;
;     asm volatile("" : "+v"(tid), "+v"(lane));
;     f32x16 Sf[2], Sb[2];
; #pragma unroll
;     for (int j = 0; j < 2; ++j)
; #pragma unroll
;         for (int i = 0; i < 16; ++i) { Sf[j][i] = 0.f; Sb[j][i] = 0.f; }
;     float dsfa = 0.f, dsfb = 0.f, pba = 0.f, pbb = 0.f;
;     unsigned lraw[8], braw[8], vraw[8];
;     {
;         const unsigned e0 = (unsigned)(((seg * SEGCH) * 64 + wid * 8) * D + h * 128 + 2 * lane);
; #pragma unroll
;         for (int i = 0; i < 8; ++i) lraw[i] = *(const unsigned*)(LFp + (e0 + (unsigned)(i * D)));
; #pragma unroll
;         for (int i = 0; i < 8; ++i) braw[i] = *(const unsigned*)(LBp + (e0 + (unsigned)(i * D)));
; #pragma unroll
;         for (int i = 0; i < 8; ++i) vraw[i] = *(const unsigned*)(Vp + (e0 + (unsigned)(i * D)));
;     }
; __global__ void __launch_bounds__(512, 2) mega(Args a) {
;     ...
;                 for (int it = bid; it < 8 * NSEG; it += gridDim.x) scan_p1_item(lds, ws, it, tid, wave, lane);
.LBB0_403:
	s_andn2_b64 vcc, exec, s[6:7]
	s_cbranch_vccnz .LBB0_652
	v_readlane_b32 s0, v255, 21
	s_and_b32 s0, 0xffff, s0
	s_cmp_gt_i32 s0, 0
	s_mov_b64 s[6:7], -1
	s_cbranch_scc0 .LBB0_465
	s_cmpk_gt_i32 s68, 0xff
	s_cbranch_scc1 .LBB0_460
	s_add_u32 s1, s30, 0x10000
	s_addc_u32 s2, s31, 0
	s_add_u32 s28, s30, 0xca00000
	s_addc_u32 s29, s31, 0
	s_add_u32 s44, s30, 0xaa00000
	s_addc_u32 s45, s31, 0
	s_lshl_b32 s34, s69, 13
	s_add_u32 s58, s30, 0xea00000
	s_addc_u32 s59, s31, 0
	s_add_u32 s35, s30, 0x1ba00000
	s_addc_u32 s38, s31, 0
	s_lshl_b32 s0, s69, 9
	s_lshl_b32 s40, s69, 3
	s_add_i32 s41, s0, 0
	s_cmp_lt_u32 s90, 64
	s_cselect_b64 s[78:79], -1, 0
	s_lshl_b32 s0, s69, 1
	s_and_b32 s20, s0, 2
	s_and_b32 s0, s90, 0xffffff80
	s_ashr_i32 s47, s90, 2
	s_add_i32 s46, s0, 0
	s_andn2_b32 s47, s47, 31
	s_cmp_lt_i32 s69, 1
	s_cselect_b64 s[80:81], -1, 0
	s_cmp_gt_i32 s69, 1
	s_cselect_b64 s[6:7], -1, 0
	s_cmp_gt_i32 s69, 2
	s_cselect_b64 s[8:9], -1, 0
	s_cmp_gt_i32 s69, 3
	s_cselect_b64 s[10:11], -1, 0
	s_cmp_gt_i32 s69, 4
	s_cselect_b64 s[12:13], -1, 0
	s_cmp_gt_i32 s69, 5
	s_cselect_b64 s[14:15], -1, 0
	s_cmp_gt_i32 s69, 6
	s_cselect_b64 s[16:17], -1, 0
	s_cmp_gt_i32 s69, 7
	s_cselect_b64 s[18:19], -1, 0
	s_or_b32 s21, s20, 1
	s_lshl_b32 s71, s69, 4
	s_lshl_b32 s26, s20, 5
	s_lshl_b32 s54, s21, 5
	s_and_b32 s0, s71, 0xffffffe0
	s_lshl_b32 s55, s20, 12
	s_lshl_b32 s60, s21, 12
	s_and_b32 s72, s68, 0xffffffe0
	s_and_b32 s98, s68, 7
	s_lshl_b32 s98, s98, 2
	s_or_b32 s72, s72, s98
	s_lshr_b32 s98, s68, 3
	s_and_b32 s98, s98, 3
	s_or_b32 s72, s72, s98
	s_branch .LBB0_408

; #define LAS __attribute__((address_space(3)))
; __device__ __forceinline__ void sgu_item(LAS unsigned char* lds, unsigned char* ws, const float* lng, const float* lnb, const float* sgb, int item, int tid, int wid, int lane) {
;     const int cidx = item >> 1, half = item & 1, tok0 = cidx * 128;
;     const int r = lane & 31, hh = lane >> 5;
;     const bf16* GV = (const bf16*)(ws + WS_GV); const bf16* U = (const bf16*)(ws + WS_U); bf16* BO = (bf16*)(ws + WS_BO); const bf16* SGW = (const bf16*)(ws + WS_SGW);
;     constexpr int L_WS = 0, L_VN = 34816, L_MU = 52224, L_RSD = 52736, L_SG = 53248, LDSG = 68;
;     LAS float* MU = (LAS float*)(lds + L_MU); LAS float* RSD = (LAS float*)(lds + L_RSD); LAS float* STG = (LAS float*)(lds + L_SG);
;     const int e = tid & 63, sp = tid >> 6;
;     u32x4 wsreg[4]; unsigned short gvs[16];
;     {
;         const int g = half * 4;
; #pragma unroll
;         for (int i = 0; i < 4; ++i) { const int idx = tid + 512 * i; wsreg[i] = *(const u32x4*)(SGW + (size_t)g * 16384 + (idx >> 4) * 128 + (idx & 15) * 8); }
; #pragma unroll
;         for (int i = 0; i < 16; ++i) gvs[i] = GV[(size_t)(tok0 + sp * 16 + i) * SGWD + g * 64 + e];
;     }
; __global__ void __launch_bounds__(512, 2) mega(Args a) {
;     ...
;                 for (int it = bid; it < 128 * 2; it += gridDim.x) sgu_item(lds, ws, ka->in[9] + l * SGWD, ka->in[10] + l * SGWD, ka->in[8] + l * 1024, it, tid, wave, lane);
.LBB0_424:
	s_load_dwordx4 s[12:15], s[66:67], 0x40
	s_load_dwordx2 s[6:7], s[66:67], 0x50
	s_lshl_b32 s8, s82, 9
	s_ashr_i32 s9, s8, 31
	s_lshl_b64 s[10:11], s[8:9], 2
	s_waitcnt lgkmcnt(0)
	s_add_u32 s8, s14, s10
	s_addc_u32 s9, s15, s11
	s_add_u32 s10, s6, s10
	s_addc_u32 s11, s7, s11
	s_lshl_b32 s6, s82, 10
	s_ashr_i32 s7, s6, 31
	v_lshlrev_b32_e32 v3, 3, v210
	s_lshl_b64 s[6:7], s[6:7], 2
	v_and_b32_e32 v4, 0x78, v3
	s_add_u32 s12, s12, s6
	v_lshlrev_b32_e32 v192, 1, v4
	s_addc_u32 s13, s13, s7
	v_lshl_add_u64 v[0:1], s[30:31], 0, v[192:193]
	s_mov_b64 s[6:7], 0x100000
	v_lshl_add_u64 v[76:77], v[0:1], 0, s[6:7]
	v_ashrrev_i32_e32 v0, 2, v210
	v_and_b32_e32 v1, 64, v254
	v_and_b32_e32 v86, -16, v0
	v_xor_b32_e32 v0, 16, v254
	v_add_u32_e32 v1, 64, v1
	s_add_u32 s6, s30, 0x13a00000
	v_cmp_lt_i32_e32 vcc, v0, v1
	s_addc_u32 s7, s31, 0
	v_lshlrev_b32_e32 v88, 1, v211
	v_mov_b32_e32 v89, v193
	v_cndmask_b32_e32 v0, v254, v0, vcc
	v_lshl_add_u64 v[90:91], s[6:7], 0, v[88:89]
	v_lshlrev_b32_e32 v89, 2, v0
	v_xor_b32_e32 v0, 32, v254
	s_lshl_b32 s1, s71, 2
	v_lshrrev_b32_e32 v2, 5, v211
	v_and_b32_e32 v5, 31, v210
	v_cmp_lt_i32_e32 vcc, v0, v1
	s_add_i32 s18, s1, 0
	s_bfe_u32 s1, s90, 0x10006
	v_and_b32_e32 v78, 0xffffff80, v3
	v_lshlrev_b32_e32 v192, 4, v211
	v_cndmask_b32_e32 v0, v254, v0, vcc
	v_and_b32_e32 v3, 56, v3
	v_or_b32_e32 v7, s0, v5
	v_lshlrev_b32_e32 v8, 3, v2
	v_lshl_or_b32 v2, v2, 2, s0
	s_lshl_b32 s0, s1, 7
	v_lshl_add_u64 v[92:93], s[6:7], 0, v[192:193]
	v_lshlrev_b32_e32 v107, 2, v0
	v_mul_u32_u24_e32 v0, 0x88, v211
	v_lshlrev_b32_e32 v192, 1, v3
	s_add_i32 s0, s0, 0
	v_add_lshl_u32 v6, v0, v86, 1
	v_lshl_add_u64 v[0:1], s[30:31], 0, v[192:193]
	s_mov_b64 s[6:7], 0x12a00000
	v_lshl_or_b32 v9, s1, 5, v5
	v_lshl_add_u32 v5, v5, 2, s0
	s_mov_b64 s[0:1], 0x18a00000
	v_lshl_add_u64 v[94:95], v[0:1], 0, s[6:7]
	v_lshl_add_u32 v109, v3, 2, 0
	v_lshl_add_u64 v[96:97], v[0:1], 0, s[0:1]
	v_add_u32_e32 v1, 0x200, v210
	v_add_u32_e32 v3, 0x400, v210
	v_add_u32_e32 v10, 0x600, v210
	v_ashrrev_i32_e32 v0, 4, v210
	v_ashrrev_i32_e32 v1, 4, v1
	v_ashrrev_i32_e32 v3, 4, v3
	v_ashrrev_i32_e32 v10, 4, v10
	v_mul_lo_u32 v0, v0, s61
	v_mul_lo_u32 v1, v1, s61
	v_mul_lo_u32 v3, v3, s61
	v_mul_lo_u32 v10, v10, s61
	v_ashrrev_i32_e32 v108, 3, v210
	v_add_lshl_u32 v0, v0, v4, 1
	v_add_lshl_u32 v1, v1, v4, 1
	v_add_lshl_u32 v3, v3, v4, 1
	v_add_lshl_u32 v4, v10, v4, 1
	v_bitop3_b32 v10, v210, -4, 60 bitop3:0xc8
	v_add_u32_e32 v80, 0x1000, v78
	v_add_u32_e32 v82, 0x2000, v78
	v_add_u32_e32 v84, 0x3000, v78
	v_mul_lo_u32 v7, v7, s61
	v_mul_u32_u24_e32 v9, 0x88, v9
	v_add_u32_e32 v111, 0, v10
	v_mul_lo_u32 v112, v108, s42
	s_lshl_b32 s19, s68, 2
	s_lshl_b32 s20, s75, 2
	v_and_b32_e32 v10, 15, v210
	v_mov_b32_e32 v11, 0x108000
	v_ashrrev_i32_e32 v79, 31, v78
	v_ashrrev_i32_e32 v81, 31, v80
	v_ashrrev_i32_e32 v83, 31, v82
	v_ashrrev_i32_e32 v85, 31, v84
	v_add_lshl_u32 v7, v7, v8, 1
	v_add_lshl_u32 v8, v9, v8, 1
	v_mul_lo_u32 v2, v2, s42
	v_add_u32_e32 v9, 0x4400, v112
	s_add_u32 s14, s12, 0x100
	v_lshl_or_b32 v192, v10, 4, v11
	v_and_b32_e32 v10, 7, v210
	v_cmp_eq_u32_e32 vcc, 0, v211
	v_lshl_add_u32 v110, v86, 2, 0
	s_addc_u32 s15, s13, 0
	v_lshl_add_u64 v[98:99], v[78:79], 1, v[192:193]
	v_lshl_add_u64 v[100:101], v[80:81], 1, v[192:193]
	v_lshl_add_u64 v[102:103], v[82:83], 1, v[192:193]
	v_lshl_add_u64 v[104:105], v[84:85], 1, v[192:193]
	v_lshlrev_b32_e32 v106, 4, v10
	s_lshl_b32 s21, s68, 6
	s_lshl_b32 s22, s75, 6
	v_add_u32_e32 v113, 64, v108
	v_ashrrev_i32_e32 v87, 31, v86
	v_add_u32_e32 v114, 0, v0
	v_add_u32_e32 v115, 0, v1
	v_add_u32_e32 v116, 0, v3
	v_add_u32_e32 v117, 0, v4
	v_add_u32_e32 v118, 0, v6
	v_add_u32_e32 v119, 0, v7
	v_add_u32_e32 v120, 0, v8
	v_add_u32_e32 v121, v5, v2
	v_add_u32_e32 v122, v109, v9
	s_and_b32 s23, s68, 7
	s_lshl_b32 s23, s23, 5
	s_lshr_b32 s98, s68, 3
	s_and_b32 s98, s98, 15
	s_lshl_b32 s98, s98, 1
	s_or_b32 s23, s23, s98
	s_lshr_b32 s98, s68, 7
	s_or_b32 s23, s23, s98
	s_lshl_b32 s19, s23, 2
	s_lshl_b32 s21, s23, 6
	s_mov_b64 s[72:73], 0x20000

; __device__ __forceinline__ unsigned xb_ld(unsigned* p)              { return __hip_atomic_load(p, __ATOMIC_RELAXED, __HIP_MEMORY_SCOPE_AGENT); }
; __device__ __forceinline__ unsigned xb_add(unsigned* p, unsigned v) { return __hip_atomic_fetch_add(p, v, __ATOMIC_RELAXED, __HIP_MEMORY_SCOPE_AGENT); }
; #define XB_SPIN(cond, bar) do { unsigned _sp = 0; while (cond) { __builtin_amdgcn_s_sleep(0); \
;     if ((++_sp & 255u) == 0u) { if (xb_ld(&(bar)[XB_TMO])) break; if (_sp > XB_SPIN_CAP) { atomicAdd(&(bar)[XB_TMO], 1u); break; } } } } while (0)
; __device__ __forceinline__ void xcd_barrier(const XcdBarrier& b) {
;     ...
;         const unsigned old = xb_add(&bar[XB_XSUB(b.x)], 1u);
;         const unsigned gen = old / nloc;
;         if (old + 1u == (gen + 1u) * nloc) {
;             __builtin_amdgcn_fence(__ATOMIC_RELEASE, "agent");
;             asm volatile("s_waitcnt vmcnt(0)" ::: "memory");
;             const unsigned og = xb_add(&bar[XB_TOP], 1u);
;             const unsigned tg = og / nx;
;             if (og + 1u == (tg + 1u) * nx) xb_add(&bar[XB_TOPGEN], 1u);
;             else XB_SPIN(xb_ld(&bar[XB_TOPGEN]) == tg, bar);
;             __builtin_amdgcn_fence(__ATOMIC_ACQUIRE, "agent");
;             xb_add(&bar[XB_XGEN(b.x)], 1u);
;             asm volatile("s_waitcnt vmcnt(0)" ::: "memory");
.LBB0_756:
	s_andn2_saveexec_b64 s[10:11], s[10:11]
	s_cbranch_execz .LBB0_776
	s_mov_b64 s[10:11], exec
	v_readlane_b32 s99, v255, 42
	s_cmp_ge_u32 s3, 18
	s_cselect_b32 s98, 18, 0
	s_sub_u32 s98, s3, s98
	s_cmp_eq_u32 s99, 0
	s_cbranch_scc1 .Lfull_l
	s_cmp_eq_u32 s98, 4
	s_cbranch_scc1 .Lnf_l4
	s_cmp_eq_u32 s98, 10
	s_cbranch_scc1 .Lnf_l4
	s_cmp_eq_u32 s98, 7
	s_cbranch_scc1 .Lnf_l4
	s_cmp_eq_u32 s98, 5
	s_cbranch_scc1 .Lnf_l
	s_cmp_eq_u32 s98, 6
	s_cbranch_scc1 .Lnf_l
	s_cmp_eq_u32 s98, 11
	s_cbranch_scc1 .Lnf_l
